# P1a row loop: global loads/stores with counted vmcnt(4) waits (store acknowledgements no longer waited each row)
# baseline (speedup 1.0000x reference)
; __device__ __forceinline__ unsigned pk2(float lo, float hi) { f32x2_c v = {lo, hi}; return __builtin_bit_cast(unsigned, __builtin_convertvector(v, bf16x2_c)); }
; __device__ __forceinline__ float wave_sum(float v) { v = row_sum16(v); return (rdlane(v, 0) + rdlane(v, 16)) + (rdlane(v, 32) + rdlane(v, 48)); }
; __device__ __forceinline__ void p1a_rows(const Args& A, char* lds, int G) {
;     ...
;         { const f32x4* xr = (const f32x4*)(A.in[I_X] + (size_t)(rb * 64 + wave * 8) * DMOD) + lane;
; #pragma unroll
;           for (int j = 0; j < 4; ++j) nx[j] = __builtin_nontemporal_load(&xr[64 * j]); }
; #pragma unroll 1
;         for (int r = 0; r < 8; ++r) { const int m = rb * 64 + wave * 8 + r;
;             f32x4 v[4]; float s = 0.f;
; #pragma unroll
;             for (int j = 0; j < 4; ++j) { v[j] = nx[j]; s += (v[j].x * v[j].x + v[j].y * v[j].y) + (v[j].z * v[j].z + v[j].w * v[j].w); }
;             if (r < 7) { const f32x4* xr = (const f32x4*)(A.in[I_X] + (size_t)(m + 1) * DMOD) + lane;
; #pragma unroll
;                 for (int j = 0; j < 4; ++j) nx[j] = __builtin_nontemporal_load(&xr[64 * j]); }
;             const float rstd = rsqrtf(wave_sum(s) * (1.f / DMOD) + RMS_EPS);
;             unsigned long long* o8 = (unsigned long long*)((unsigned char*)A.out + (size_t)m * 4096) + lane;
; #pragma unroll
;             for (int j = 0; j < 4; ++j) { const f32x4 h = v[j] * rstd * mul[j] + add[j]; o8[64 * j] = (unsigned long long)pk2(h.x, h.y) | ((unsigned long long)pk2(h.z, h.w) << 32); } }
.LBB0_386:
	s_or_b64 exec, exec, s[6:7]
	v_lshl_add_u32 v0, s19, 6, v81
	v_ashrrev_i32_e32 v1, 31, v0
	v_lshlrev_b64 v[0:1], 12, v[0:1]
	v_lshl_add_u64 v[0:1], v[64:65], 0, v[0:1]
	s_waitcnt lgkmcnt(0)
	s_barrier
	global_load_dwordx4 v[44:47], v[0:1], off nt
	global_load_dwordx4 v[40:43], v[0:1], off offset:1024 nt
	global_load_dwordx4 v[36:39], v[0:1], off offset:2048 nt
	global_load_dwordx4 v[32:35], v[0:1], off offset:3072 nt
	ds_read_b128 v[0:3], v80
	ds_read_b128 v[4:7], v80 offset:1024
	ds_read_b128 v[8:11], v80 offset:4096
	ds_read_b128 v[12:15], v80 offset:5120
	ds_read_b128 v[16:19], v80 offset:2048
	ds_read_b128 v[20:23], v80 offset:3072
	ds_read_b128 v[24:27], v80 offset:6144
	ds_read_b128 v[28:31], v80 offset:7168
	s_mov_b32 s6, 0
	s_waitcnt vmcnt(0)
	s_branch .LBB0_388
.LBB0_387:
	v_mul_f32_e32 v79, v45, v45
	v_mul_f32_e32 v87, v47, v47
	v_fmac_f32_e32 v79, v44, v44
	v_fmac_f32_e32 v87, v46, v46
	v_add_f32_e32 v79, v79, v87
	v_mul_f32_e32 v87, v41, v41
	v_mul_f32_e32 v88, v43, v43
	v_fmac_f32_e32 v87, v40, v40
	v_fmac_f32_e32 v88, v42, v42
	v_add_f32_e32 v87, v87, v88
	v_add_f32_e32 v79, v79, v87
	v_mul_f32_e32 v87, v37, v37
	v_mul_f32_e32 v88, v39, v39
	v_fmac_f32_e32 v87, v36, v36
	v_fmac_f32_e32 v88, v38, v38
	v_add_f32_e32 v87, v87, v88
	v_add_f32_e32 v79, v87, v79
	v_mul_f32_e32 v87, v33, v33
	v_mul_f32_e32 v88, v35, v35
	v_fmac_f32_e32 v87, v32, v32
	v_fmac_f32_e32 v88, v34, v34
	v_add_f32_e32 v87, v87, v88
	v_add_f32_e32 v79, v87, v79
	v_mov_b32_e32 v87, v79
	s_add_i32 s6, s6, 1
	s_cmp_eq_u32 s6, 8
	v_mov_b32_dpp v87, v87 quad_perm:[1,0,3,2] row_mask:0xf bank_mask:0xf
	v_add_f32_e32 v79, v79, v87
	v_mov_b32_e32 v87, v79
	s_nop 1
	v_mov_b32_dpp v87, v87 quad_perm:[2,3,0,1] row_mask:0xf bank_mask:0xf
	v_add_f32_e32 v79, v79, v87
	v_mov_b32_e32 v87, v79
	s_nop 1
	v_mov_b32_dpp v87, v87 row_half_mirror row_mask:0xf bank_mask:0xf
	v_add_f32_e32 v79, v79, v87
	v_mov_b32_e32 v87, v79
	s_nop 1
	v_mov_b32_dpp v87, v87 row_mirror row_mask:0xf bank_mask:0xf
	v_add_f32_e32 v79, v79, v87
	s_nop 0
	v_readlane_b32 s7, v79, 16
	v_readlane_b32 s10, v79, 48
	v_readlane_b32 s8, v79, 0
	v_readlane_b32 s9, v79, 32
	v_mov_b32_e32 v88, s7
	v_mov_b32_e32 v89, s10
	v_pk_add_f32 v[88:89], s[8:9], v[88:89]
	s_nop 0
	v_add_f32_e32 v79, v88, v89
	v_fmamk_f32 v79, v79, 0x3a800000, v85
	v_mul_f32_e32 v87, 0x4b800000, v79
	v_cmp_gt_f32_e32 vcc, s18, v79
	s_nop 1
	v_cndmask_b32_e32 v79, v79, v87, vcc
	v_rsq_f32_e32 v79, v79
	s_nop 0
	v_mul_f32_e32 v87, 0x45800000, v79
	v_cndmask_b32_e32 v88, v79, v87, vcc
	v_ashrrev_i32_e32 v79, 31, v78
	v_pk_mul_f32 v[44:45], v[44:45], v[88:89] op_sel_hi:[1,0]
	v_pk_mul_f32 v[46:47], v[46:47], v[88:89] op_sel_hi:[1,0]
	v_pk_mul_f32 v[40:41], v[40:41], v[88:89] op_sel_hi:[1,0]
	v_pk_mul_f32 v[42:43], v[42:43], v[88:89] op_sel_hi:[1,0]
	v_pk_mul_f32 v[36:37], v[36:37], v[88:89] op_sel_hi:[1,0]
	v_pk_mul_f32 v[38:39], v[38:39], v[88:89] op_sel_hi:[1,0]
	v_pk_mul_f32 v[32:33], v[32:33], v[88:89] op_sel_hi:[1,0]
	v_pk_mul_f32 v[34:35], v[34:35], v[88:89] op_sel_hi:[1,0]
	v_lshlrev_b64 v[78:79], 12, v[78:79]
	v_pk_fma_f32 v[46:47], v[2:3], v[46:47], v[10:11]
	v_pk_fma_f32 v[44:45], v[0:1], v[44:45], v[8:9]
	v_pk_fma_f32 v[42:43], v[6:7], v[42:43], v[14:15]
	v_pk_fma_f32 v[40:41], v[4:5], v[40:41], v[12:13]
	v_pk_fma_f32 v[38:39], v[18:19], v[38:39], v[26:27]
	v_pk_fma_f32 v[36:37], v[16:17], v[36:37], v[24:25]
	v_pk_fma_f32 v[34:35], v[22:23], v[34:35], v[30:31]
	v_pk_fma_f32 v[32:33], v[20:21], v[32:33], v[28:29]
	v_lshl_add_u64 v[78:79], v[66:67], 0, v[78:79]
	v_cvt_pk_bf16_f32 v44, v44, v45
	v_cvt_pk_bf16_f32 v45, v46, v47
	v_cvt_pk_bf16_f32 v40, v40, v41
	v_cvt_pk_bf16_f32 v41, v42, v43
	v_cvt_pk_bf16_f32 v36, v36, v37
	v_cvt_pk_bf16_f32 v37, v38, v39
	v_cvt_pk_bf16_f32 v32, v32, v33
	v_cvt_pk_bf16_f32 v33, v34, v35
	global_store_dwordx2 v[78:79], v[44:45], off
	global_store_dwordx2 v[78:79], v[40:41], off offset:512
	global_store_dwordx2 v[78:79], v[36:37], off offset:1024
	global_store_dwordx2 v[78:79], v[32:33], off offset:1536
	s_waitcnt vmcnt(4) lgkmcnt(0)
	v_mov_b32_e32 v44, v48
	v_mov_b32_e32 v45, v49
	v_mov_b32_e32 v46, v50
	v_mov_b32_e32 v47, v51
	v_mov_b32_e32 v40, v52
	v_mov_b32_e32 v41, v53
	v_mov_b32_e32 v42, v54
	v_mov_b32_e32 v43, v55
	v_mov_b32_e32 v36, v56
	v_mov_b32_e32 v37, v57
	v_mov_b32_e32 v38, v58
	v_mov_b32_e32 v39, v59
	v_mov_b32_e32 v32, v60
	v_mov_b32_e32 v33, v61
	v_mov_b32_e32 v34, v62
	v_mov_b32_e32 v35, v63
	s_cbranch_scc1 .LBB0_382
.LBB0_388:
	v_add_u32_e32 v78, s6, v84
	s_cmp_eq_u32 s6, 7
	s_waitcnt vmcnt(4) lgkmcnt(0)
	v_mov_b32_e32 v48, v44
	v_mov_b32_e32 v49, v45
	v_mov_b32_e32 v50, v46
	v_mov_b32_e32 v51, v47
	v_mov_b32_e32 v52, v40
	v_mov_b32_e32 v53, v41
	v_mov_b32_e32 v54, v42
	v_mov_b32_e32 v55, v43
	v_mov_b32_e32 v56, v36
	v_mov_b32_e32 v57, v37
	v_mov_b32_e32 v58, v38
	v_mov_b32_e32 v59, v39
	v_mov_b32_e32 v60, v32
	v_mov_b32_e32 v61, v33
	v_mov_b32_e32 v62, v34
	v_mov_b32_e32 v63, v35
	s_cbranch_scc1 .LBB0_387
	v_add_u32_e32 v48, 1, v78
	v_ashrrev_i32_e32 v49, 31, v48
	v_lshlrev_b64 v[48:49], 12, v[48:49]
	v_lshl_add_u64 v[88:89], v[64:65], 0, v[48:49]
	global_load_dwordx4 v[48:51], v[88:89], off nt
	global_load_dwordx4 v[52:55], v[88:89], off offset:1024 nt
	global_load_dwordx4 v[56:59], v[88:89], off offset:2048 nt
	global_load_dwordx4 v[60:63], v[88:89], off offset:3072 nt
	s_branch .LBB0_387
